# grid barrier followers poll the top-level generation word directly (one poll hop less)
# speedup vs baseline: 1.0052x; 1.0009x over previous
; __device__ __forceinline__ unsigned xb_ld(unsigned* p)              { return __hip_atomic_load(p, __ATOMIC_RELAXED, __HIP_MEMORY_SCOPE_AGENT); }
; __device__ __forceinline__ unsigned xb_add(unsigned* p, unsigned v) { return __hip_atomic_fetch_add(p, v, __ATOMIC_RELAXED, __HIP_MEMORY_SCOPE_AGENT); }
; #define XB_SPIN(cond, bar) do { unsigned _sp = 0; while (cond) { __builtin_amdgcn_s_sleep(1); \
;     if ((++_sp & 255u) == 0u) { if (xb_ld(&(bar)[XB_TMO])) break; if (_sp > XB_SPIN_CAP) { atomicAdd(&(bar)[XB_TMO], 1u); break; } } } } while (0)
; __device__ __forceinline__ void xcd_barrier(const XcdBarrier& b) {
;     ...
;         const unsigned old = xb_add(&bar[XB_XSUB(b.x)], 1u);
;         const unsigned gen = old / nloc;
;         if (old + 1u == (gen + 1u) * nloc) {
;             __builtin_amdgcn_fence(__ATOMIC_RELEASE, "agent");
;             asm volatile("s_waitcnt vmcnt(0)" ::: "memory");
;             const unsigned og = xb_add(&bar[XB_TOP], 1u);
;             const unsigned tg = og / nx;
;             if (og + 1u == (tg + 1u) * nx) xb_add(&bar[XB_TOPGEN], 1u);
;             else XB_SPIN(xb_ld(&bar[XB_TOPGEN]) == tg, bar);
;             __builtin_amdgcn_fence(__ATOMIC_ACQUIRE, "agent");
;             xb_add(&bar[XB_XGEN(b.x)], 1u);
;             asm volatile("s_waitcnt vmcnt(0)" ::: "memory");
;         } else {
;             XB_SPIN(xb_ld(&bar[XB_XGEN(b.x)]) == gen, bar);
.LBB0_97:
	s_or_b64 exec, exec, s[10:11]
	v_cvt_f32_u32_e32 v5, v3
	s_waitcnt vmcnt(0)
	v_readfirstlane_b32 s0, v4
	v_sub_u32_e32 v4, 0, v3
	v_rcp_iflag_f32_e32 v5, v5
	v_add_u32_e32 v6, s0, v2
	v_mul_f32_e32 v5, 0x4f7ffffe, v5
	v_cvt_u32_f32_e32 v5, v5
	v_mul_lo_u32 v2, v4, v5
	v_mul_hi_u32 v2, v5, v2
	v_add_u32_e32 v2, v5, v2
	v_mul_hi_u32 v2, v6, v2
	v_mul_lo_u32 v4, v2, v3
	v_sub_u32_e32 v4, v6, v4
	v_add_u32_e32 v5, 1, v2
	v_cmp_ge_u32_e32 vcc, v4, v3
	s_nop 1
	v_cndmask_b32_e32 v2, v2, v5, vcc
	v_sub_u32_e32 v5, v4, v3
	v_cndmask_b32_e32 v4, v4, v5, vcc
	v_add_u32_e32 v5, 1, v2
	v_cmp_ge_u32_e32 vcc, v4, v3
	v_add_u32_e32 v4, 1, v6
	s_nop 0
	v_cndmask_b32_e32 v2, v2, v5, vcc
	v_mul_lo_u32 v5, v3, v2
	v_add_u32_e32 v3, v5, v3
	v_cmp_ne_u32_e32 vcc, v4, v3
	s_and_saveexec_b64 s[0:1], vcc
	s_xor_b64 s[8:9], exec, s[0:1]
	s_cbranch_execz .LBB0_111
	s_waitcnt lgkmcnt(0)
	buffer_inv sc1
	v_mov_b32_e32 v2, 0
	v_mov_b32_e32 v1, 0x3500
	global_load_dword v1, v1, s[50:51] sc1
	s_add_u32 s12, s50, 0x3500
	s_addc_u32 s13, s51, 0
	s_waitcnt vmcnt(0)
	v_cmp_eq_u32_e32 vcc, v1, v2
	s_and_saveexec_b64 s[10:11], vcc
	s_cbranch_execz .LBB0_110
	s_mov_b32 s0, 1
	s_mov_b64 s[14:15], 0
	v_mov_b32_e32 v1, 0
	s_branch .LBB0_101

; __device__ __forceinline__ unsigned xb_ld(unsigned* p)              { return __hip_atomic_load(p, __ATOMIC_RELAXED, __HIP_MEMORY_SCOPE_AGENT); }
; __device__ __forceinline__ unsigned xb_add(unsigned* p, unsigned v) { return __hip_atomic_fetch_add(p, v, __ATOMIC_RELAXED, __HIP_MEMORY_SCOPE_AGENT); }
; #define XB_SPIN(cond, bar) do { unsigned _sp = 0; while (cond) { __builtin_amdgcn_s_sleep(1); \
;     if ((++_sp & 255u) == 0u) { if (xb_ld(&(bar)[XB_TMO])) break; if (_sp > XB_SPIN_CAP) { atomicAdd(&(bar)[XB_TMO], 1u); break; } } } } while (0)
; __device__ __forceinline__ void xcd_barrier(const XcdBarrier& b) {
;     ...
;         const unsigned old = xb_add(&bar[XB_XSUB(b.x)], 1u);
;         const unsigned gen = old / nloc;
;         if (old + 1u == (gen + 1u) * nloc) {
;             __builtin_amdgcn_fence(__ATOMIC_RELEASE, "agent");
;             asm volatile("s_waitcnt vmcnt(0)" ::: "memory");
;             const unsigned og = xb_add(&bar[XB_TOP], 1u);
;             const unsigned tg = og / nx;
;             if (og + 1u == (tg + 1u) * nx) xb_add(&bar[XB_TOPGEN], 1u);
;             else XB_SPIN(xb_ld(&bar[XB_TOPGEN]) == tg, bar);
;             __builtin_amdgcn_fence(__ATOMIC_ACQUIRE, "agent");
;             xb_add(&bar[XB_XGEN(b.x)], 1u);
;             asm volatile("s_waitcnt vmcnt(0)" ::: "memory");
;         } else {
;             XB_SPIN(xb_ld(&bar[XB_XGEN(b.x)]) == gen, bar);
.LBB0_249:
	s_or_b64 exec, exec, s[10:11]
	v_cvt_f32_u32_e32 v5, v3
	s_waitcnt vmcnt(0)
	v_readfirstlane_b32 s0, v4
	v_sub_u32_e32 v4, 0, v3
	v_rcp_iflag_f32_e32 v5, v5
	v_add_u32_e32 v6, s0, v2
	v_mul_f32_e32 v5, 0x4f7ffffe, v5
	v_cvt_u32_f32_e32 v5, v5
	v_mul_lo_u32 v2, v4, v5
	v_mul_hi_u32 v2, v5, v2
	v_add_u32_e32 v2, v5, v2
	v_mul_hi_u32 v2, v6, v2
	v_mul_lo_u32 v4, v2, v3
	v_sub_u32_e32 v4, v6, v4
	v_add_u32_e32 v5, 1, v2
	v_cmp_ge_u32_e32 vcc, v4, v3
	s_nop 1
	v_cndmask_b32_e32 v2, v2, v5, vcc
	v_sub_u32_e32 v5, v4, v3
	v_cndmask_b32_e32 v4, v4, v5, vcc
	v_add_u32_e32 v5, 1, v2
	v_cmp_ge_u32_e32 vcc, v4, v3
	v_add_u32_e32 v4, 1, v6
	s_nop 0
	v_cndmask_b32_e32 v2, v2, v5, vcc
	v_mul_lo_u32 v5, v3, v2
	v_add_u32_e32 v3, v5, v3
	v_cmp_ne_u32_e32 vcc, v4, v3
	s_and_saveexec_b64 s[0:1], vcc
	s_xor_b64 s[8:9], exec, s[0:1]
	s_cbranch_execz .LBB0_263
	s_waitcnt lgkmcnt(0)
	buffer_inv sc1
	v_mov_b32_e32 v2, 1
	v_mov_b32_e32 v1, 0x3500
	global_load_dword v1, v1, s[50:51] sc1
	s_add_u32 s12, s50, 0x3500
	s_addc_u32 s13, s51, 0
	s_waitcnt vmcnt(0)
	v_cmp_eq_u32_e32 vcc, v1, v2
	s_and_saveexec_b64 s[10:11], vcc
	s_cbranch_execz .LBB0_262
	s_mov_b32 s0, 1
	s_mov_b64 s[14:15], 0
	v_mov_b32_e32 v1, 0
	s_branch .LBB0_253

; __device__ __forceinline__ unsigned xb_ld(unsigned* p)              { return __hip_atomic_load(p, __ATOMIC_RELAXED, __HIP_MEMORY_SCOPE_AGENT); }
; __device__ __forceinline__ unsigned xb_add(unsigned* p, unsigned v) { return __hip_atomic_fetch_add(p, v, __ATOMIC_RELAXED, __HIP_MEMORY_SCOPE_AGENT); }
; #define XB_SPIN(cond, bar) do { unsigned _sp = 0; while (cond) { __builtin_amdgcn_s_sleep(1); \
;     if ((++_sp & 255u) == 0u) { if (xb_ld(&(bar)[XB_TMO])) break; if (_sp > XB_SPIN_CAP) { atomicAdd(&(bar)[XB_TMO], 1u); break; } } } } while (0)
; __device__ __forceinline__ void xcd_barrier(const XcdBarrier& b) {
;     ...
;         const unsigned old = xb_add(&bar[XB_XSUB(b.x)], 1u);
;         const unsigned gen = old / nloc;
;         if (old + 1u == (gen + 1u) * nloc) {
;             __builtin_amdgcn_fence(__ATOMIC_RELEASE, "agent");
;             asm volatile("s_waitcnt vmcnt(0)" ::: "memory");
;             const unsigned og = xb_add(&bar[XB_TOP], 1u);
;             const unsigned tg = og / nx;
;             if (og + 1u == (tg + 1u) * nx) xb_add(&bar[XB_TOPGEN], 1u);
;             else XB_SPIN(xb_ld(&bar[XB_TOPGEN]) == tg, bar);
;             __builtin_amdgcn_fence(__ATOMIC_ACQUIRE, "agent");
;             xb_add(&bar[XB_XGEN(b.x)], 1u);
;             asm volatile("s_waitcnt vmcnt(0)" ::: "memory");
;         } else {
;             XB_SPIN(xb_ld(&bar[XB_XGEN(b.x)]) == gen, bar);
.LBB0_455:
	s_or_b64 exec, exec, s[10:11]
	v_cvt_f32_u32_e32 v5, v3
	s_waitcnt vmcnt(0)
	v_readfirstlane_b32 s0, v4
	v_sub_u32_e32 v4, 0, v3
	v_rcp_iflag_f32_e32 v5, v5
	v_add_u32_e32 v6, s0, v2
	v_mul_f32_e32 v5, 0x4f7ffffe, v5
	v_cvt_u32_f32_e32 v5, v5
	v_mul_lo_u32 v2, v4, v5
	v_mul_hi_u32 v2, v5, v2
	v_add_u32_e32 v2, v5, v2
	v_mul_hi_u32 v2, v6, v2
	v_mul_lo_u32 v4, v2, v3
	v_sub_u32_e32 v4, v6, v4
	v_add_u32_e32 v5, 1, v2
	v_cmp_ge_u32_e32 vcc, v4, v3
	s_nop 1
	v_cndmask_b32_e32 v2, v2, v5, vcc
	v_sub_u32_e32 v5, v4, v3
	v_cndmask_b32_e32 v4, v4, v5, vcc
	v_add_u32_e32 v5, 1, v2
	v_cmp_ge_u32_e32 vcc, v4, v3
	v_add_u32_e32 v4, 1, v6
	s_nop 0
	v_cndmask_b32_e32 v2, v2, v5, vcc
	v_mul_lo_u32 v5, v3, v2
	v_add_u32_e32 v3, v5, v3
	v_cmp_ne_u32_e32 vcc, v4, v3
	s_and_saveexec_b64 s[0:1], vcc
	s_xor_b64 s[8:9], exec, s[0:1]
	s_cbranch_execz .LBB0_469
	s_waitcnt lgkmcnt(0)
	buffer_inv sc1
	v_mov_b32_e32 v2, 2
	v_mov_b32_e32 v1, 0x3500
	global_load_dword v1, v1, s[50:51] sc1
	s_add_u32 s12, s50, 0x3500
	s_addc_u32 s13, s51, 0
	s_waitcnt vmcnt(0)
	v_cmp_eq_u32_e32 vcc, v1, v2
	s_and_saveexec_b64 s[10:11], vcc
	s_cbranch_execz .LBB0_468
	s_mov_b32 s0, 1
	s_mov_b64 s[14:15], 0
	v_mov_b32_e32 v1, 0
	s_branch .LBB0_459

; __device__ __forceinline__ unsigned xb_ld(unsigned* p)              { return __hip_atomic_load(p, __ATOMIC_RELAXED, __HIP_MEMORY_SCOPE_AGENT); }
; __device__ __forceinline__ unsigned xb_add(unsigned* p, unsigned v) { return __hip_atomic_fetch_add(p, v, __ATOMIC_RELAXED, __HIP_MEMORY_SCOPE_AGENT); }
; #define XB_SPIN(cond, bar) do { unsigned _sp = 0; while (cond) { __builtin_amdgcn_s_sleep(1); \
;     if ((++_sp & 255u) == 0u) { if (xb_ld(&(bar)[XB_TMO])) break; if (_sp > XB_SPIN_CAP) { atomicAdd(&(bar)[XB_TMO], 1u); break; } } } } while (0)
; __device__ __forceinline__ void xcd_barrier(const XcdBarrier& b) {
;     ...
;         const unsigned old = xb_add(&bar[XB_XSUB(b.x)], 1u);
;         const unsigned gen = old / nloc;
;         if (old + 1u == (gen + 1u) * nloc) {
;             __builtin_amdgcn_fence(__ATOMIC_RELEASE, "agent");
;             asm volatile("s_waitcnt vmcnt(0)" ::: "memory");
;             const unsigned og = xb_add(&bar[XB_TOP], 1u);
;             const unsigned tg = og / nx;
;             if (og + 1u == (tg + 1u) * nx) xb_add(&bar[XB_TOPGEN], 1u);
;             else XB_SPIN(xb_ld(&bar[XB_TOPGEN]) == tg, bar);
;             __builtin_amdgcn_fence(__ATOMIC_ACQUIRE, "agent");
;             xb_add(&bar[XB_XGEN(b.x)], 1u);
;             asm volatile("s_waitcnt vmcnt(0)" ::: "memory");
;         } else {
;             XB_SPIN(xb_ld(&bar[XB_XGEN(b.x)]) == gen, bar);
.LBB0_1016:
	s_or_b64 exec, exec, s[8:9]
	v_cvt_f32_u32_e32 v5, v3
	s_waitcnt vmcnt(0)
	v_readfirstlane_b32 s0, v4
	v_sub_u32_e32 v4, 0, v3
	v_rcp_iflag_f32_e32 v5, v5
	v_add_u32_e32 v6, s0, v2
	v_mul_f32_e32 v5, 0x4f7ffffe, v5
	v_cvt_u32_f32_e32 v5, v5
	v_mul_lo_u32 v2, v4, v5
	v_mul_hi_u32 v2, v5, v2
	v_add_u32_e32 v2, v5, v2
	v_mul_hi_u32 v2, v6, v2
	v_mul_lo_u32 v4, v2, v3
	v_sub_u32_e32 v4, v6, v4
	v_add_u32_e32 v5, 1, v2
	v_cmp_ge_u32_e32 vcc, v4, v3
	s_nop 1
	v_cndmask_b32_e32 v2, v2, v5, vcc
	v_sub_u32_e32 v5, v4, v3
	v_cndmask_b32_e32 v4, v4, v5, vcc
	v_add_u32_e32 v5, 1, v2
	v_cmp_ge_u32_e32 vcc, v4, v3
	v_add_u32_e32 v4, 1, v6
	s_nop 0
	v_cndmask_b32_e32 v2, v2, v5, vcc
	v_mul_lo_u32 v5, v3, v2
	v_add_u32_e32 v3, v5, v3
	v_cmp_ne_u32_e32 vcc, v4, v3
	s_and_saveexec_b64 s[0:1], vcc
	s_xor_b64 s[6:7], exec, s[0:1]
	s_cbranch_execz .LBB0_1030
	s_waitcnt lgkmcnt(0)
	buffer_inv sc1
	v_mov_b32_e32 v2, 3
	v_mov_b32_e32 v1, 0x3500
	global_load_dword v1, v1, s[50:51] sc1
	s_add_u32 s10, s50, 0x3500
	s_addc_u32 s11, s51, 0
	s_waitcnt vmcnt(0)
	v_cmp_eq_u32_e32 vcc, v1, v2
	s_and_saveexec_b64 s[8:9], vcc
	s_cbranch_execz .LBB0_1029
	s_mov_b32 s0, 1
	s_mov_b64 s[12:13], 0
	v_mov_b32_e32 v1, 0
	s_branch .LBB0_1020

; __device__ __forceinline__ unsigned xb_ld(unsigned* p)              { return __hip_atomic_load(p, __ATOMIC_RELAXED, __HIP_MEMORY_SCOPE_AGENT); }
; __device__ __forceinline__ unsigned xb_add(unsigned* p, unsigned v) { return __hip_atomic_fetch_add(p, v, __ATOMIC_RELAXED, __HIP_MEMORY_SCOPE_AGENT); }
; #define XB_SPIN(cond, bar) do { unsigned _sp = 0; while (cond) { __builtin_amdgcn_s_sleep(1); \
;     if ((++_sp & 255u) == 0u) { if (xb_ld(&(bar)[XB_TMO])) break; if (_sp > XB_SPIN_CAP) { atomicAdd(&(bar)[XB_TMO], 1u); break; } } } } while (0)
; __device__ __forceinline__ void xcd_barrier(const XcdBarrier& b) {
;     ...
;         const unsigned old = xb_add(&bar[XB_XSUB(b.x)], 1u);
;         const unsigned gen = old / nloc;
;         if (old + 1u == (gen + 1u) * nloc) {
;             __builtin_amdgcn_fence(__ATOMIC_RELEASE, "agent");
;             asm volatile("s_waitcnt vmcnt(0)" ::: "memory");
;             const unsigned og = xb_add(&bar[XB_TOP], 1u);
;             const unsigned tg = og / nx;
;             if (og + 1u == (tg + 1u) * nx) xb_add(&bar[XB_TOPGEN], 1u);
;             else XB_SPIN(xb_ld(&bar[XB_TOPGEN]) == tg, bar);
;             __builtin_amdgcn_fence(__ATOMIC_ACQUIRE, "agent");
;             xb_add(&bar[XB_XGEN(b.x)], 1u);
;             asm volatile("s_waitcnt vmcnt(0)" ::: "memory");
;         } else {
;             XB_SPIN(xb_ld(&bar[XB_XGEN(b.x)]) == gen, bar);
.LBB0_1096:
	s_or_b64 exec, exec, s[10:11]
	v_cvt_f32_u32_e32 v5, v3
	s_waitcnt vmcnt(0)
	v_readfirstlane_b32 s0, v4
	v_sub_u32_e32 v4, 0, v3
	v_rcp_iflag_f32_e32 v5, v5
	v_add_u32_e32 v6, s0, v2
	v_mul_f32_e32 v5, 0x4f7ffffe, v5
	v_cvt_u32_f32_e32 v5, v5
	v_mul_lo_u32 v2, v4, v5
	v_mul_hi_u32 v2, v5, v2
	v_add_u32_e32 v2, v5, v2
	v_mul_hi_u32 v2, v6, v2
	v_mul_lo_u32 v4, v2, v3
	v_sub_u32_e32 v4, v6, v4
	v_add_u32_e32 v5, 1, v2
	v_cmp_ge_u32_e32 vcc, v4, v3
	s_nop 1
	v_cndmask_b32_e32 v2, v2, v5, vcc
	v_sub_u32_e32 v5, v4, v3
	v_cndmask_b32_e32 v4, v4, v5, vcc
	v_add_u32_e32 v5, 1, v2
	v_cmp_ge_u32_e32 vcc, v4, v3
	v_add_u32_e32 v4, 1, v6
	s_nop 0
	v_cndmask_b32_e32 v2, v2, v5, vcc
	v_mul_lo_u32 v5, v3, v2
	v_add_u32_e32 v3, v5, v3
	v_cmp_ne_u32_e32 vcc, v4, v3
	s_and_saveexec_b64 s[0:1], vcc
	s_xor_b64 s[8:9], exec, s[0:1]
	s_cbranch_execz .LBB0_1110
	s_waitcnt lgkmcnt(0)
	buffer_inv sc1
	v_mov_b32_e32 v2, 4
	v_mov_b32_e32 v1, 0x3500
	global_load_dword v1, v1, s[50:51] sc1
	s_add_u32 s12, s50, 0x3500
	s_addc_u32 s13, s51, 0
	s_waitcnt vmcnt(0)
	v_cmp_eq_u32_e32 vcc, v1, v2
	s_and_saveexec_b64 s[10:11], vcc
	s_cbranch_execz .LBB0_1109
	s_mov_b32 s0, 1
	s_mov_b64 s[14:15], 0
	v_mov_b32_e32 v1, 0
	s_branch .LBB0_1100
